# grid barrier: every workgroup issues an early L2 writeback (buffer_wbl2 sc1) before its arrival atomic so the XCD leader's writeback has little left
# baseline (speedup 1.0000x reference)
; __device__ __forceinline__ unsigned xb_add(unsigned* p, unsigned v) { return __hip_atomic_fetch_add(p, v, __ATOMIC_RELAXED, __HIP_MEMORY_SCOPE_AGENT); }
; __device__ __forceinline__ void xcd_barrier(const XcdBarrier& b) {
;     ...
;     if (threadIdx.x == 0) {
;         unsigned* bar = b.bar;
;         __builtin_amdgcn_s_waitcnt(0);
;         unsigned nloc = b.st[0], nx = b.st[1];
;         if (nloc == 0u) { xcd_barrier_complete(bar, b.x, nloc, nx); b.st[0] = nloc; b.st[1] = nx; }
;         const unsigned old = xb_add(&bar[XB_XSUB(b.x)], 1u);
;         const unsigned gen = old / nloc;
.LBB0_50:
	s_mov_b64 s[4:5], exec
	v_mbcnt_lo_u32_b32 v1, s4, 0
	v_mbcnt_hi_u32_b32 v1, s5, v1
	v_cmp_eq_u32_e32 vcc, 0, v1
	s_and_saveexec_b64 s[0:1], vcc
	s_cbranch_execz .LBB0_52
	s_bcnt1_i32_b64 s2, s[4:5]
	v_readlane_b32 s4, v253, 27
	v_mov_b32_e32 v3, s2
	v_readlane_b32 s5, v253, 28
	s_nop 4
	buffer_wbl2 sc1
	global_atomic_add v3, v97, v3, s[4:5] sc0
